# attention: output-gate loads issued with the item's first loads; K/V block prefetch distance 2 (second landing buffer, parity)
# baseline (speedup 1.0000x reference)
.LBB0_188:
	s_or_b64 exec, exec, s[4:5]
	v_lshlrev_b32_e32 v176, 1, v125
	v_lshl_add_u64 v[32:33], v[126:127], 0, v[176:177]
	v_mov_b64_e32 v[46:47], v[156:157]
	v_mov_b64_e32 v[44:45], v[158:159]
	v_mov_b64_e32 v[42:43], v[160:161]
	v_mov_b64_e32 v[40:41], v[162:163]
	v_mov_b64_e32 v[38:39], v[164:165]
	v_mov_b64_e32 v[36:37], v[166:167]
	v_mov_b64_e32 v[34:35], v[168:169]
	s_nop 0
	v_mov_b64_e32 v[32:33], v[170:171]
	v_readlane_b32 s2, v254, 13
	v_readlane_b32 s3, v254, 14
	v_mov_b32_e32 v125, v177
	s_waitcnt vmcnt(7)
	v_lshlrev_b32_e32 v50, 16, v46
	v_and_b32_e32 v51, 0xffff0000, v46
	v_mul_f32_e32 v46, 0xbfb8aa3b, v50
	v_exp_f32_e32 v46, v46
	v_mov_b64_e32 v[48:49], s[2:3]
	v_mad_i64_i32 v[48:49], s[2:3], v136, s67, v[48:49]
	v_add_f32_e32 v46, 1.0, v46
	v_rcp_f32_e32 v52, v46
	v_mul_f32_e32 v46, 0xbfb8aa3b, v51
	v_exp_f32_e32 v46, v46
	v_lshl_add_u64 v[48:49], v[48:49], 0, v[124:125]
	v_add_f32_e32 v46, 1.0, v46
	v_rcp_f32_e32 v53, v46
	s_nop 0
	v_pk_mul_f32 v[50:51], v[52:53], v[50:51]
	s_nop 0
	v_pk_mul_f32 v[16:17], v[16:17], v[50:51]
	s_nop 0
	v_cvt_pk_bf16_f32 v46, v16, v17
	v_lshlrev_b32_e32 v16, 16, v47
	v_and_b32_e32 v17, 0xffff0000, v47
	v_mul_f32_e32 v47, 0xbfb8aa3b, v16
	v_exp_f32_e32 v47, v47
	s_nop 0
	v_add_f32_e32 v47, 1.0, v47
	v_rcp_f32_e32 v50, v47
	v_mul_f32_e32 v47, 0xbfb8aa3b, v17
	v_exp_f32_e32 v47, v47
	s_nop 0
	v_add_f32_e32 v47, 1.0, v47
	v_rcp_f32_e32 v51, v47
	s_nop 0
	v_pk_mul_f32 v[16:17], v[50:51], v[16:17]
	s_nop 0
	v_pk_mul_f32 v[16:17], v[18:19], v[16:17]
	s_waitcnt vmcnt(6)
	v_lshlrev_b32_e32 v18, 16, v44
	v_and_b32_e32 v19, 0xffff0000, v44
	v_mul_f32_e32 v44, 0xbfb8aa3b, v18
	v_exp_f32_e32 v44, v44
	v_cvt_pk_bf16_f32 v47, v16, v17
	v_lshl_add_u64 v[16:17], v[48:49], 0, v[176:177]
	global_store_dwordx2 v[16:17], v[46:47], off
	v_add_f32_e32 v44, 1.0, v44
	v_rcp_f32_e32 v46, v44
	v_mul_f32_e32 v44, 0xbfb8aa3b, v19
	v_exp_f32_e32 v44, v44
	s_nop 0
	v_add_f32_e32 v44, 1.0, v44
	v_rcp_f32_e32 v47, v44
	s_nop 0
	v_pk_mul_f32 v[18:19], v[46:47], v[18:19]
	s_nop 0
	v_pk_mul_f32 v[18:19], v[20:21], v[18:19]
	v_lshlrev_b32_e32 v20, 16, v45
	v_cvt_pk_bf16_f32 v18, v18, v19
	v_mul_f32_e32 v19, 0xbfb8aa3b, v20
	v_exp_f32_e32 v19, v19
	v_and_b32_e32 v21, 0xffff0000, v45
	v_add_f32_e32 v19, 1.0, v19
	v_rcp_f32_e32 v44, v19
	v_mul_f32_e32 v19, 0xbfb8aa3b, v21
	v_exp_f32_e32 v19, v19
	s_nop 0
	v_add_f32_e32 v19, 1.0, v19
	v_rcp_f32_e32 v45, v19
	s_nop 0
	v_pk_mul_f32 v[20:21], v[44:45], v[20:21]
	s_nop 0
	v_pk_mul_f32 v[20:21], v[22:23], v[20:21]
	s_nop 0
	v_cvt_pk_bf16_f32 v19, v20, v21
	global_store_dwordx2 v[16:17], v[18:19], off offset:16
	s_waitcnt vmcnt(7)
	v_lshlrev_b32_e32 v18, 16, v42
	v_and_b32_e32 v19, 0xffff0000, v42
	v_mul_f32_e32 v20, 0xbfb8aa3b, v18
	v_mul_f32_e32 v21, 0xbfb8aa3b, v19
	v_exp_f32_e32 v20, v20
	v_exp_f32_e32 v21, v21
	v_add_f32_e32 v20, 1.0, v20
	v_add_f32_e32 v21, 1.0, v21
	v_rcp_f32_e32 v20, v20
	v_rcp_f32_e32 v21, v21
	s_nop 0
	v_pk_mul_f32 v[18:19], v[20:21], v[18:19]
	s_nop 0
	v_pk_mul_f32 v[18:19], v[24:25], v[18:19]
	v_lshlrev_b32_e32 v20, 16, v43
	v_cvt_pk_bf16_f32 v18, v18, v19
	v_mul_f32_e32 v19, 0xbfb8aa3b, v20
	v_exp_f32_e32 v19, v19
	v_and_b32_e32 v21, 0xffff0000, v43
	v_add_f32_e32 v19, 1.0, v19
	v_rcp_f32_e32 v22, v19
	v_mul_f32_e32 v19, 0xbfb8aa3b, v21
	v_exp_f32_e32 v19, v19
	s_nop 0
	v_add_f32_e32 v19, 1.0, v19
	v_rcp_f32_e32 v23, v19
	s_nop 0
	v_pk_mul_f32 v[20:21], v[22:23], v[20:21]
	s_nop 0
	v_pk_mul_f32 v[20:21], v[26:27], v[20:21]
	s_nop 0
	v_cvt_pk_bf16_f32 v19, v20, v21
	global_store_dwordx2 v[16:17], v[18:19], off offset:32
	s_waitcnt vmcnt(7)
	v_lshlrev_b32_e32 v18, 16, v40
	v_and_b32_e32 v19, 0xffff0000, v40
	v_mul_f32_e32 v20, 0xbfb8aa3b, v18
	v_mul_f32_e32 v21, 0xbfb8aa3b, v19
	v_exp_f32_e32 v20, v20
	v_exp_f32_e32 v21, v21
	v_add_f32_e32 v20, 1.0, v20
	v_add_f32_e32 v21, 1.0, v21
	v_rcp_f32_e32 v20, v20
	v_rcp_f32_e32 v21, v21
	s_nop 0
	v_pk_mul_f32 v[18:19], v[20:21], v[18:19]
	s_nop 0
	v_pk_mul_f32 v[18:19], v[28:29], v[18:19]
	v_lshlrev_b32_e32 v20, 16, v41
	v_cvt_pk_bf16_f32 v18, v18, v19
	v_mul_f32_e32 v19, 0xbfb8aa3b, v20
	v_exp_f32_e32 v19, v19
	v_and_b32_e32 v21, 0xffff0000, v41
	v_add_f32_e32 v19, 1.0, v19
	v_rcp_f32_e32 v22, v19
	v_mul_f32_e32 v19, 0xbfb8aa3b, v21
	v_exp_f32_e32 v19, v19
	s_nop 0
	v_add_f32_e32 v19, 1.0, v19
	v_rcp_f32_e32 v23, v19
	s_nop 0
	v_pk_mul_f32 v[20:21], v[22:23], v[20:21]
	s_nop 0
	v_pk_mul_f32 v[20:21], v[30:31], v[20:21]
	s_nop 0
	v_cvt_pk_bf16_f32 v19, v20, v21
	global_store_dwordx2 v[16:17], v[18:19], off offset:48
	s_waitcnt vmcnt(7)
	v_lshlrev_b32_e32 v18, 16, v38
	v_and_b32_e32 v19, 0xffff0000, v38
	v_mul_f32_e32 v20, 0xbfb8aa3b, v18
	v_mul_f32_e32 v21, 0xbfb8aa3b, v19
	v_exp_f32_e32 v20, v20
	v_exp_f32_e32 v21, v21
	v_add_f32_e32 v20, 1.0, v20
	v_add_f32_e32 v21, 1.0, v21
	v_rcp_f32_e32 v20, v20
	v_rcp_f32_e32 v21, v21
	s_nop 0
	v_pk_mul_f32 v[18:19], v[20:21], v[18:19]
	s_nop 0
	v_pk_mul_f32 v[0:1], v[0:1], v[18:19]
	v_lshlrev_b32_e32 v18, 16, v39
	v_cvt_pk_bf16_f32 v0, v0, v1
	v_mul_f32_e32 v1, 0xbfb8aa3b, v18
	v_exp_f32_e32 v1, v1
	v_and_b32_e32 v19, 0xffff0000, v39
	v_add_f32_e32 v1, 1.0, v1
	v_rcp_f32_e32 v20, v1
	v_mul_f32_e32 v1, 0xbfb8aa3b, v19
	v_exp_f32_e32 v1, v1
	s_nop 0
	v_add_f32_e32 v1, 1.0, v1
	v_rcp_f32_e32 v21, v1
	s_nop 0
	v_pk_mul_f32 v[18:19], v[20:21], v[18:19]
	s_nop 0
	v_pk_mul_f32 v[2:3], v[2:3], v[18:19]
	s_nop 0
	v_cvt_pk_bf16_f32 v1, v2, v3
	global_store_dwordx2 v[16:17], v[0:1], off offset:64
	s_waitcnt vmcnt(7)
	v_lshlrev_b32_e32 v0, 16, v36
	v_and_b32_e32 v1, 0xffff0000, v36
	v_mul_f32_e32 v2, 0xbfb8aa3b, v0
	v_mul_f32_e32 v3, 0xbfb8aa3b, v1
	v_exp_f32_e32 v2, v2
	v_exp_f32_e32 v3, v3
	v_add_f32_e32 v2, 1.0, v2
	v_add_f32_e32 v3, 1.0, v3
	v_rcp_f32_e32 v2, v2
	v_rcp_f32_e32 v3, v3
	s_nop 0
	v_pk_mul_f32 v[0:1], v[2:3], v[0:1]
	s_nop 0
	v_pk_mul_f32 v[0:1], v[4:5], v[0:1]
	v_lshlrev_b32_e32 v2, 16, v37
	v_cvt_pk_bf16_f32 v0, v0, v1
	v_mul_f32_e32 v1, 0xbfb8aa3b, v2
	v_exp_f32_e32 v1, v1
	v_and_b32_e32 v3, 0xffff0000, v37
	v_add_f32_e32 v1, 1.0, v1
	v_rcp_f32_e32 v4, v1
	v_mul_f32_e32 v1, 0xbfb8aa3b, v3
	v_exp_f32_e32 v1, v1
	s_nop 0
	v_add_f32_e32 v1, 1.0, v1
	v_rcp_f32_e32 v5, v1
	s_nop 0
	v_pk_mul_f32 v[2:3], v[4:5], v[2:3]
	s_nop 0
	v_pk_mul_f32 v[2:3], v[6:7], v[2:3]
	s_nop 0
	v_cvt_pk_bf16_f32 v1, v2, v3
	global_store_dwordx2 v[16:17], v[0:1], off offset:80
	s_waitcnt vmcnt(7)
	v_lshlrev_b32_e32 v0, 16, v34
	v_and_b32_e32 v1, 0xffff0000, v34
	v_mul_f32_e32 v2, 0xbfb8aa3b, v0
	v_mul_f32_e32 v3, 0xbfb8aa3b, v1
	v_exp_f32_e32 v2, v2
	v_exp_f32_e32 v3, v3
	v_add_f32_e32 v2, 1.0, v2
	v_add_f32_e32 v3, 1.0, v3
	v_rcp_f32_e32 v2, v2
	v_rcp_f32_e32 v3, v3
	s_nop 0
	v_pk_mul_f32 v[0:1], v[2:3], v[0:1]
	s_nop 0
	v_pk_mul_f32 v[0:1], v[8:9], v[0:1]
	v_lshlrev_b32_e32 v2, 16, v35
	v_cvt_pk_bf16_f32 v0, v0, v1
	v_mul_f32_e32 v1, 0xbfb8aa3b, v2
	v_exp_f32_e32 v1, v1
	v_and_b32_e32 v3, 0xffff0000, v35
	v_add_f32_e32 v1, 1.0, v1
	v_rcp_f32_e32 v4, v1
	v_mul_f32_e32 v1, 0xbfb8aa3b, v3
	v_exp_f32_e32 v1, v1
	s_nop 0
	v_add_f32_e32 v1, 1.0, v1
	v_rcp_f32_e32 v5, v1
	s_nop 0
	v_pk_mul_f32 v[2:3], v[4:5], v[2:3]
	s_nop 0
	v_pk_mul_f32 v[2:3], v[10:11], v[2:3]
	s_nop 0
	v_cvt_pk_bf16_f32 v1, v2, v3
	global_store_dwordx2 v[16:17], v[0:1], off offset:96
	s_waitcnt vmcnt(7)
	v_lshlrev_b32_e32 v0, 16, v32
	v_and_b32_e32 v1, 0xffff0000, v32
	v_mul_f32_e32 v2, 0xbfb8aa3b, v0
	v_mul_f32_e32 v3, 0xbfb8aa3b, v1
	v_exp_f32_e32 v2, v2
	v_exp_f32_e32 v3, v3
	v_add_f32_e32 v2, 1.0, v2
	v_add_f32_e32 v3, 1.0, v3
	v_rcp_f32_e32 v2, v2
	v_rcp_f32_e32 v3, v3
	s_nop 0
	v_pk_mul_f32 v[0:1], v[2:3], v[0:1]
	s_nop 0
	v_pk_mul_f32 v[0:1], v[12:13], v[0:1]
	v_lshlrev_b32_e32 v2, 16, v33
	v_cvt_pk_bf16_f32 v0, v0, v1
	v_mul_f32_e32 v1, 0xbfb8aa3b, v2
	v_exp_f32_e32 v1, v1
	v_and_b32_e32 v3, 0xffff0000, v33
	v_add_f32_e32 v1, 1.0, v1
	v_rcp_f32_e32 v4, v1
	v_mul_f32_e32 v1, 0xbfb8aa3b, v3
	v_exp_f32_e32 v1, v1
	s_nop 0
	v_add_f32_e32 v1, 1.0, v1
	v_rcp_f32_e32 v5, v1
	s_nop 0
	v_pk_mul_f32 v[2:3], v[4:5], v[2:3]
	s_nop 0
	v_pk_mul_f32 v[2:3], v[14:15], v[2:3]
	s_nop 0
	v_cvt_pk_bf16_f32 v1, v2, v3
	global_store_dwordx2 v[16:17], v[0:1], off offset:112
	s_waitcnt vmcnt(8)

.LBB0_293:
	v_mov_b32_e32 v92, v206
	v_mov_b32_e32 v125, v177
	v_ashrrev_i32_e32 v0, 6, v92
	v_lshl_add_u32 v6, s20, 3, v0
	v_mov_b32_e32 v0, v206
	v_and_b32_e32 v138, 0xff, v6
	v_and_b32_e32 v137, 31, v0
	v_bfe_u32 v4, v0, 5, 1
	v_lshlrev_b32_e32 v5, 5, v138
	v_lshlrev_b32_e32 v0, 3, v6
	v_and_b32_e32 v7, 0xffffe000, v0
	v_or_b32_e32 v8, v5, v137
	v_ashrrev_i32_e32 v6, 2, v6
	v_or_b32_e32 v136, v8, v7
	v_mov_b64_e32 v[0:1], s[76:77]
	v_and_b32_e32 v9, 0xc0, v6
	v_mad_i64_i32 v[2:3], s[2:3], v136, s13, v[0:1]
	v_lshlrev_b32_e32 v124, 1, v9
	v_lshl_add_u64 v[126:127], v[2:3], 0, v[124:125]
	v_lshlrev_b32_e32 v176, 4, v4
	v_lshl_add_u64 v[2:3], v[126:127], 0, v[176:177]
	v_mad_i64_i32 v[0:1], s[2:3], v7, s13, v[0:1]
	global_load_dwordx4 v[48:51], v[2:3], off
	global_load_dwordx4 v[52:55], v[2:3], off offset:32
	global_load_dwordx4 v[56:59], v[2:3], off offset:64
	global_load_dwordx4 v[60:63], v[2:3], off offset:96
	v_and_b32_e32 v2, 0xffffffc0, v6
	v_lshl_add_u64 v[0:1], v[0:1], 0, v[124:125]
	v_lshl_add_u64 v[128:129], v[0:1], 0, v[176:177]
	v_ashrrev_i32_e32 v3, 31, v2
	v_mul_u32_u24_e32 v0, 0xa00, v8
	v_lshlrev_b64 v[6:7], 14, v[2:3]
	v_lshlrev_b32_e32 v176, 1, v0
	v_lshl_add_u64 v[8:9], v[128:129], 0, v[176:177]
	v_lshl_add_u64 v[6:7], s[98:99], 0, v[6:7]
	v_lshlrev_b32_e32 v176, 6, v138
	global_load_dwordx4 v[0:3], v[8:9], off offset:512
	global_load_dwordx4 v[28:31], v[8:9], off offset:544
	global_load_dwordx4 v[20:23], v[8:9], off offset:576
	global_load_dwordx4 v[24:27], v[8:9], off offset:608
	v_lshl_add_u64 v[8:9], v[6:7], 0, v[176:177]
	v_lshlrev_b32_e32 v176, 5, v4
	v_lshl_add_u64 v[8:9], v[8:9], 0, v[176:177]
	v_lshlrev_b32_e32 v10, 14, v137
	v_mov_b32_e32 v11, v177
	v_lshlrev_b32_e32 v12, 13, v137
	v_lshl_add_u64 v[10:11], v[8:9], 0, v[10:11]
	global_load_dwordx4 v[36:39], v[10:11], off offset:16
	global_load_dwordx4 v[16:19], v[10:11], off
	v_or_b32_e32 v10, 0x40000, v12
	v_lshlrev_b32_e32 v130, 1, v10
	v_mov_b32_e32 v131, v177
	v_lshl_add_u64 v[8:9], v[8:9], 0, v[130:131]
	global_load_dwordx4 v[40:43], v[8:9], off offset:16
	global_load_dwordx4 v[44:47], v[8:9], off
	v_lshl_add_u64 v[132:133], v[6:7], 0, v[176:177]
	v_cmp_ne_u32_e64 s[36:37], 0, v138
	v_lshlrev_b32_e32 v134, 1, v12
	s_and_saveexec_b64 s[2:3], s[36:37]
	s_xor_b64 s[2:3], exec, s[2:3]
	s_cbranch_execz .LBB0_295
	v_subrev_u32_e32 v176, 32, v5
	v_or_b32_e32 v5, v176, v137
	v_mad_u64_u32 v[6:7], s[4:5], v5, s13, v[128:129]
	global_load_dwordx4 v[32:35], v[6:7], off offset:512
	global_load_dwordx4 v[88:91], v[6:7], off offset:544
	global_load_dwordx4 v[84:87], v[6:7], off offset:576
	global_load_dwordx4 v[80:83], v[6:7], off offset:608
	v_lshl_add_u64 v[6:7], v[176:177], 1, v[132:133]
	v_mov_b32_e32 v135, v177
	v_lshl_add_u64 v[8:9], v[6:7], 0, v[134:135]
	v_lshl_add_u64 v[6:7], v[6:7], 0, v[130:131]
	global_load_dwordx4 v[64:67], v[8:9], off offset:16
	global_load_dwordx4 v[76:79], v[8:9], off
	global_load_dwordx4 v[68:71], v[6:7], off offset:16
	global_load_dwordx4 v[72:75], v[6:7], off
	v_cmp_lt_u32_e32 vcc, 1, v138
	s_cbranch_vccz .Latt_pre_skip
	v_subrev_u32_e32 v252, 32, v176
	v_mov_b32_e32 v253, v177
	v_or_b32_e32 v6, v252, v137
	v_mad_u64_u32 v[6:7], s[4:5], v6, s13, v[128:129]
	global_load_dwordx4 v[220:223], v[6:7], off offset:512
	global_load_dwordx4 v[224:227], v[6:7], off offset:544
	global_load_dwordx4 v[228:231], v[6:7], off offset:576
	global_load_dwordx4 v[232:235], v[6:7], off offset:608
	v_lshl_add_u64 v[6:7], v[252:253], 1, v[132:133]
	v_lshl_add_u64 v[8:9], v[6:7], 0, v[134:135]
	v_lshl_add_u64 v[6:7], v[6:7], 0, v[130:131]
	global_load_dwordx4 v[236:239], v[8:9], off offset:16
	global_load_dwordx4 v[240:243], v[8:9], off
	global_load_dwordx4 v[244:247], v[6:7], off offset:16
	global_load_dwordx4 v[248:251], v[6:7], off
.Latt_pre_skip:
.LBB0_295:
	s_andn2_saveexec_b64 s[2:3], s[2:3]
	s_cbranch_execz .LBB0_297
	s_waitcnt vmcnt(0)
	v_mov_b64_e32 v[82:83], v[26:27]
	v_mov_b64_e32 v[86:87], v[22:23]
	v_mov_b64_e32 v[90:91], v[30:31]
	v_mov_b64_e32 v[34:35], v[2:3]
	v_mov_b64_e32 v[80:81], v[24:25]
	v_mov_b64_e32 v[84:85], v[20:21]
	v_mov_b64_e32 v[88:89], v[28:29]
	v_mov_b64_e32 v[32:33], v[0:1]
	v_mov_b32_e32 v68, v40
	v_mov_b32_e32 v69, v41
	v_mov_b32_e32 v64, v36
	v_mov_b32_e32 v65, v37
	v_mov_b32_e32 v72, v44
	v_mov_b32_e32 v73, v45
	v_mov_b32_e32 v76, v16
	v_mov_b32_e32 v77, v17
	v_mov_b32_e32 v70, v42
	v_mov_b32_e32 v71, v43
	v_mov_b32_e32 v66, v38
	v_mov_b32_e32 v67, v39
	v_mov_b32_e32 v74, v46
	v_mov_b32_e32 v75, v47
	v_mov_b32_e32 v78, v18
	v_mov_b32_e32 v79, v19
.LBB0_297:
	s_or_b64 exec, exec, s[2:3]
	v_and_b32_e32 v6, 64, v210
	v_xor_b32_e32 v5, 32, v210
	v_add_u32_e32 v6, 64, v6
	v_cmp_lt_i32_e32 vcc, v5, v6
	v_lshlrev_b32_e32 v125, 2, v4
	v_cmp_lt_u32_e64 s[38:39], v125, v137
	v_cndmask_b32_e32 v5, v210, v5, vcc
	v_lshlrev_b32_e32 v139, 2, v5
	v_cmp_eq_u32_e32 vcc, 0, v4
	v_lshlrev_b32_e32 v172, 1, v125
	v_mov_b32_e32 v173, 0
	v_lshl_add_u64 v[174:175], v[126:127], 0, v[172:173]
	global_load_dwordx2 v[156:157], v[174:175], off offset:1024
	global_load_dwordx2 v[158:159], v[174:175], off offset:1040
	global_load_dwordx2 v[160:161], v[174:175], off offset:1056
	global_load_dwordx2 v[162:163], v[174:175], off offset:1072
	global_load_dwordx2 v[164:165], v[174:175], off offset:1088
	global_load_dwordx2 v[166:167], v[174:175], off offset:1104
	global_load_dwordx2 v[168:169], v[174:175], off offset:1120
	global_load_dwordx2 v[170:171], v[174:175], off offset:1136
	s_waitcnt vmcnt(0)
	v_mfma_f32_32x32x16_bf16 v[0:15], v[0:3], v[48:51], 0
	v_mfma_f32_32x32x16_bf16 v[0:15], v[28:31], v[52:55], v[0:15]
	v_mfma_f32_32x32x16_bf16 v[0:15], v[20:23], v[56:59], v[0:15]
	v_mfma_f32_32x32x16_bf16 v[0:15], v[24:27], v[60:63], v[0:15]
	s_nop 11
	v_mul_f32_e32 v0, 0x3e38aa3b, v0
	v_min_f32_e32 v0, 0x42700000, v0
	v_exp_f32_e32 v20, v0
	s_nop 0
	v_add_f32_e32 v20, 1.0, v20
	v_log_f32_e32 v21, v20
	s_nop 0
	v_sub_f32_e32 v0, v0, v21
	v_cndmask_b32_e64 v20, v217, v0, s[38:39]
	v_mul_f32_e32 v0, 0x3e38aa3b, v1
	v_min_f32_e32 v0, 0x42700000, v0
	v_exp_f32_e32 v1, v0
	v_cndmask_b32_e64 v23, 0, v21, s[38:39]
	v_or_b32_e32 v21, 1, v125
	v_cmp_lt_u32_e64 s[38:39], v21, v137
	v_add_f32_e32 v1, 1.0, v1
	v_log_f32_e32 v1, v1
	s_nop 0
	v_sub_f32_e32 v0, v0, v1
	v_cndmask_b32_e64 v22, v217, v0, s[38:39]
	v_mul_f32_e32 v0, 0x3e38aa3b, v2
	v_min_f32_e32 v0, 0x42700000, v0
	v_cndmask_b32_e64 v21, 0, v1, s[38:39]
	v_exp_f32_e32 v1, v0
	v_or_b32_e32 v2, 2, v125
	v_cmp_lt_u32_e64 s[38:39], v2, v137
	v_or_b32_e32 v2, 3, v125
	v_add_f32_e32 v1, 1.0, v1
	v_log_f32_e32 v1, v1
	s_nop 0
	v_sub_f32_e32 v0, v0, v1
	v_cndmask_b32_e64 v25, v217, v0, s[38:39]
	v_mul_f32_e32 v0, 0x3e38aa3b, v3
	v_min_f32_e32 v0, 0x42700000, v0
	v_cndmask_b32_e64 v24, 0, v1, s[38:39]
	v_exp_f32_e32 v1, v0
	v_cmp_lt_u32_e64 s[38:39], v2, v137
	v_or_b32_e32 v2, 8, v125
	v_or_b32_e32 v3, 9, v125
	v_add_f32_e32 v1, 1.0, v1
	v_log_f32_e32 v1, v1
	s_nop 0
	v_sub_f32_e32 v0, v0, v1
	v_cndmask_b32_e64 v27, v217, v0, s[38:39]
	v_mul_f32_e32 v0, 0x3e38aa3b, v4
	v_min_f32_e32 v0, 0x42700000, v0
	v_cndmask_b32_e64 v26, 0, v1, s[38:39]
	v_exp_f32_e32 v1, v0
	v_cmp_lt_u32_e64 s[38:39], v2, v137
	v_or_b32_e32 v4, 10, v125
	v_add_f32_e32 v1, 1.0, v1
	v_log_f32_e32 v1, v1
	s_nop 0
	v_sub_f32_e32 v0, v0, v1
	v_cndmask_b32_e64 v28, v217, v0, s[38:39]
	v_mul_f32_e32 v0, 0x3e38aa3b, v5
	v_min_f32_e32 v0, 0x42700000, v0
	v_cndmask_b32_e64 v2, 0, v1, s[38:39]
	v_exp_f32_e32 v1, v0
	v_cmp_lt_u32_e64 s[38:39], v3, v137
	v_or_b32_e32 v5, 18, v125
	v_add_f32_e32 v1, 1.0, v1
	v_log_f32_e32 v1, v1
	s_nop 0
	v_sub_f32_e32 v0, v0, v1
	v_cndmask_b32_e64 v29, v217, v0, s[38:39]
	v_cndmask_b32_e64 v0, 0, v1, s[38:39]
	v_mul_f32_e32 v1, 0x3e38aa3b, v6
	v_min_f32_e32 v1, 0x42700000, v1
	v_exp_f32_e32 v3, v1
	v_cmp_lt_u32_e64 s[38:39], v4, v137
	v_or_b32_e32 v4, 11, v125
	v_add_f32_e32 v3, 1.0, v3
	v_log_f32_e32 v3, v3
	s_nop 0
	v_sub_f32_e32 v1, v1, v3
	v_cndmask_b32_e64 v31, v217, v1, s[38:39]
	v_mul_f32_e32 v1, 0x3e38aa3b, v7
	v_min_f32_e32 v1, 0x42700000, v1
	v_cndmask_b32_e64 v30, 0, v3, s[38:39]
	v_exp_f32_e32 v3, v1
	v_cmp_lt_u32_e64 s[38:39], v4, v137
	v_or_b32_e32 v4, 16, v125
	v_or_b32_e32 v7, 25, v125
	v_add_f32_e32 v3, 1.0, v3
	v_log_f32_e32 v3, v3
	s_nop 0
	v_sub_f32_e32 v1, v1, v3
	v_cndmask_b32_e64 v96, v217, v1, s[38:39]
	v_mul_f32_e32 v1, 0x3e38aa3b, v8
	v_min_f32_e32 v1, 0x42700000, v1
	v_cndmask_b32_e64 v97, 0, v3, s[38:39]
	v_exp_f32_e32 v3, v1
	v_cmp_lt_u32_e64 s[38:39], v4, v137
	v_or_b32_e32 v4, 17, v125
	v_add_f32_e32 v8, v30, v97
	v_add_f32_e32 v3, 1.0, v3
	v_log_f32_e32 v3, v3
	s_nop 0
	v_sub_f32_e32 v1, v1, v3
	v_cndmask_b32_e64 v98, v217, v1, s[38:39]
	v_mul_f32_e32 v1, 0x3e38aa3b, v9
	v_min_f32_e32 v1, 0x42700000, v1
	v_cndmask_b32_e64 v6, 0, v3, s[38:39]
	v_exp_f32_e32 v3, v1
	v_cmp_lt_u32_e64 s[38:39], v4, v137
	v_add_f32_e32 v3, 1.0, v3
	v_log_f32_e32 v3, v3
	s_nop 0
	v_sub_f32_e32 v1, v1, v3
	v_cndmask_b32_e64 v99, v217, v1, s[38:39]
	v_mul_f32_e32 v1, 0x3e38aa3b, v10
	v_min_f32_e32 v1, 0x42700000, v1
	v_cndmask_b32_e64 v4, 0, v3, s[38:39]
	v_exp_f32_e32 v3, v1
	v_cmp_lt_u32_e64 s[38:39], v5, v137
	v_or_b32_e32 v5, 19, v125
	v_add_f32_e32 v3, 1.0, v3
	v_log_f32_e32 v3, v3
	s_nop 0
	v_sub_f32_e32 v1, v1, v3
	v_cndmask_b32_e64 v100, v217, v1, s[38:39]
	v_mul_f32_e32 v1, 0x3e38aa3b, v11
	v_min_f32_e32 v1, 0x42700000, v1
	v_cndmask_b32_e64 v101, 0, v3, s[38:39]
	v_exp_f32_e32 v3, v1
	v_cmp_lt_u32_e64 s[38:39], v5, v137
	v_or_b32_e32 v5, 24, v125
	v_add_f32_e32 v3, 1.0, v3
	v_log_f32_e32 v3, v3
	s_nop 0
	v_sub_f32_e32 v1, v1, v3
	v_cndmask_b32_e64 v102, v217, v1, s[38:39]
	v_mul_f32_e32 v1, 0x3e38aa3b, v12
	v_min_f32_e32 v1, 0x42700000, v1
	v_cndmask_b32_e64 v103, 0, v3, s[38:39]
	v_exp_f32_e32 v3, v1
	v_cmp_lt_u32_e64 s[38:39], v5, v137
	v_add_f32_e32 v10, v101, v103
	v_add_f32_e32 v3, 1.0, v3
	v_log_f32_e32 v3, v3
	s_nop 0
	v_sub_f32_e32 v1, v1, v3
	v_cndmask_b32_e64 v12, v217, v1, s[38:39]
	v_cndmask_b32_e64 v1, 0, v3, s[38:39]
	v_mul_f32_e32 v3, 0x3e38aa3b, v13
	v_min_f32_e32 v3, 0x42700000, v3
	v_exp_f32_e32 v5, v3
	v_cmp_lt_u32_e64 s[38:39], v7, v137
	v_or_b32_e32 v7, 26, v125
	v_add_f32_e32 v5, 1.0, v5
	v_log_f32_e32 v5, v5
	s_nop 0
	v_sub_f32_e32 v3, v3, v5
	v_cndmask_b32_e64 v13, v217, v3, s[38:39]
	v_mul_f32_e32 v3, 0x3e38aa3b, v14
	v_min_f32_e32 v3, 0x42700000, v3
	v_cndmask_b32_e64 v104, 0, v5, s[38:39]
	v_exp_f32_e32 v5, v3
	v_cmp_lt_u32_e64 s[38:39], v7, v137
	v_or_b32_e32 v7, 27, v125
	v_add_f32_e32 v5, 1.0, v5
	v_log_f32_e32 v5, v5
	s_nop 0
	v_sub_f32_e32 v3, v3, v5
	v_cndmask_b32_e64 v14, v217, v3, s[38:39]
	v_mul_f32_e32 v3, 0x3e38aa3b, v15
	v_min_f32_e32 v3, 0x42700000, v3
	v_cndmask_b32_e64 v105, 0, v5, s[38:39]
	v_exp_f32_e32 v5, v3
	v_cmp_lt_u32_e64 s[38:39], v7, v137
	v_add_f32_e32 v7, v1, v104
	v_add_f32_e32 v5, 1.0, v5
	v_log_f32_e32 v5, v5
	s_nop 0
	v_sub_f32_e32 v3, v3, v5
	v_cndmask_b32_e64 v15, v217, v3, s[38:39]
	v_cndmask_b32_e64 v106, 0, v5, s[38:39]
	v_add_f32_e32 v3, v23, v21
	v_add_f32_e32 v5, v24, v26
	v_add_f32_e32 v93, v3, v5
	v_add_f32_e32 v5, v105, v106
	v_pk_add_f32 v[6:7], v[6:7], v[4:5]
	ds_bpermute_b32 v11, v139, v7
	ds_bpermute_b32 v94, v139, v93
	s_waitcnt lgkmcnt(1)
	v_pk_add_f32 v[6:7], v[6:7], v[10:11]
	ds_bpermute_b32 v9, v139, v6
	v_mov_b32_e32 v3, v6
	v_mov_b32_e32 v1, v7
	v_pk_add_f32 v[2:3], v[2:3], v[0:1]
	s_waitcnt lgkmcnt(0)
	v_pk_add_f32 v[2:3], v[2:3], v[8:9]
	ds_bpermute_b32 v1, v139, v2
	v_add_f32_e32 v2, v2, v3
	s_waitcnt lgkmcnt(0)
	v_add_f32_e32 v95, v2, v1
	v_cndmask_b32_e32 v1, 0, v1, vcc
	v_add_f32_e32 v1, v1, v3
	v_cndmask_b32_e32 v2, 0, v94, vcc
	v_add_f32_e32 v1, 0, v1
	v_add_f32_e32 v2, v2, v95
	v_sub_f32_e32 v3, v96, v1
	v_add_f32_e32 v1, v97, v1
	v_add_f32_e32 v2, 0, v2
	v_sub_f32_e32 v10, v31, v1
	v_add_f32_e32 v1, v30, v1
	v_sub_f32_e32 v5, v27, v2
	v_add_f32_e32 v2, v26, v2
	v_add_f32_e32 v0, v0, v1
	v_sub_f32_e32 v6, v25, v2
	v_add_f32_e32 v2, v24, v2
	v_sub_f32_e32 v0, v28, v0
	v_sub_f32_e32 v8, v22, v2
	v_add_f32_e32 v2, v21, v2
	v_exp_f32_e32 v21, v0
	v_cndmask_b32_e32 v0, 0, v9, vcc
	v_add_f32_e32 v0, v0, v7
	v_add_f32_e32 v0, 0, v0
	v_sub_f32_e32 v2, v20, v2
	v_sub_f32_e32 v20, v29, v1
	v_sub_f32_e32 v1, v102, v0
	v_add_f32_e32 v0, v103, v0
	v_exp_f32_e32 v96, v1
	v_sub_f32_e32 v1, v100, v0
	v_add_f32_e32 v0, v101, v0
	v_exp_f32_e32 v97, v1
	v_sub_f32_e32 v1, v99, v0
	v_add_f32_e32 v0, v4, v0
	v_sub_f32_e32 v0, v98, v0
	v_exp_f32_e32 v98, v0
	v_add_f32_e32 v0, 0, v11
	v_cndmask_b32_e32 v0, 0, v0, vcc
	v_exp_f32_e32 v5, v5
	v_exp_f32_e32 v6, v6
	v_exp_f32_e32 v8, v8
	v_exp_f32_e32 v2, v2
	v_exp_f32_e32 v3, v3
	v_exp_f32_e32 v10, v10
	v_exp_f32_e32 v20, v20
	v_exp_f32_e32 v99, v1
	v_sub_f32_e32 v1, v15, v0
	v_add_f32_e32 v0, v0, v106
	v_exp_f32_e32 v100, v1
	v_sub_f32_e32 v1, v14, v0
	v_add_f32_e32 v0, v105, v0
	v_exp_f32_e32 v101, v1
	v_sub_f32_e32 v1, v13, v0
	v_add_f32_e32 v0, v104, v0
	v_sub_f32_e32 v0, v12, v0
	v_exp_f32_e32 v102, v1
	v_exp_f32_e32 v103, v0
	v_cvt_pk_bf16_f32 v0, v2, v8
	v_cvt_pk_bf16_f32 v1, v6, v5
	v_cvt_pk_bf16_f32 v2, v21, v20
	v_cvt_pk_bf16_f32 v3, v10, v3
	s_nop 1
	v_mfma_f32_32x32x16_bf16 v[16:31], v[16:19], v[0:3], 0
	v_mfma_f32_32x32x16_bf16 v[0:15], v[44:47], v[0:3], 0
	v_cvt_pk_bf16_f32 v44, v98, v99
	v_cvt_pk_bf16_f32 v45, v97, v96
	v_cvt_pk_bf16_f32 v46, v103, v102
	v_cvt_pk_bf16_f32 v47, v101, v100
	s_nop 1
	v_mfma_f32_32x32x16_bf16 v[16:31], v[36:39], v[44:47], v[16:31]
	v_mfma_f32_32x32x16_bf16 v[0:15], v[40:43], v[44:47], v[0:15]
	s_and_saveexec_b64 s[4:5], s[36:37]
	s_cbranch_execz .LBB0_188
	v_add_f32_e32 v36, v93, v95
	v_add_f32_e32 v36, v36, v94
	s_mov_b32 s2, 0x43170000
	v_cmp_lt_f32_e64 s[36:37], s2, v36
	s_cmp_eq_u64 s[36:37], exec
	s_cbranch_scc1 .LBB0_188
	v_lshrrev_b32_e32 v37, 6, v92
	v_add_f32_e32 v140, 0, v36
	v_add_u16_e32 v36, s9, v37
	v_and_b32_e32 v36, 0xff, v36
	v_not_b32_e32 v37, 63
	v_lshl_add_u32 v176, v36, 5, v37
	s_mov_b64 s[38:39], 0
	s_mov_b32 s100, 0
	s_branch .LBB0_301
.LBB0_300:
	s_or_b64 exec, exec, s[2:3]
	s_and_b64 s[2:3], exec, s[6:7]
	s_or_b64 s[38:39], s[2:3], s[38:39]
	s_waitcnt vmcnt(8)
	s_cmp_eq_u32 s100, 0
	s_cbranch_scc0 .Latt_m1
	v_mov_b64_e32 v[32:33], v[220:221]
	v_mov_b64_e32 v[34:35], v[222:223]
	v_mov_b64_e32 v[88:89], v[224:225]
	v_mov_b64_e32 v[90:91], v[226:227]
	v_mov_b64_e32 v[84:85], v[228:229]
	v_mov_b64_e32 v[86:87], v[230:231]
	v_mov_b64_e32 v[80:81], v[232:233]
	v_mov_b64_e32 v[82:83], v[234:235]
	v_mov_b64_e32 v[64:65], v[236:237]
	v_mov_b64_e32 v[66:67], v[238:239]
	v_mov_b64_e32 v[76:77], v[240:241]
	v_mov_b64_e32 v[78:79], v[242:243]
	v_mov_b64_e32 v[68:69], v[244:245]
	v_mov_b64_e32 v[70:71], v[246:247]
	v_mov_b64_e32 v[72:73], v[248:249]
	v_mov_b64_e32 v[74:75], v[250:251]
	s_branch .Latt_m2
.Latt_m1:
	v_mov_b64_e32 v[32:33], v[104:105]
	v_mov_b64_e32 v[34:35], v[106:107]
	v_mov_b64_e32 v[88:89], v[100:101]
	v_mov_b64_e32 v[90:91], v[102:103]
	v_mov_b64_e32 v[84:85], v[96:97]
	v_mov_b64_e32 v[86:87], v[98:99]
	v_mov_b64_e32 v[80:81], v[92:93]
	v_mov_b64_e32 v[82:83], v[94:95]
	v_mov_b64_e32 v[64:65], v[108:109]
	v_mov_b64_e32 v[66:67], v[110:111]
	v_mov_b64_e32 v[76:77], v[116:117]
	v_mov_b64_e32 v[78:79], v[118:119]
	v_mov_b64_e32 v[68:69], v[112:113]
	v_mov_b64_e32 v[70:71], v[114:115]
	v_mov_b64_e32 v[72:73], v[120:121]
	v_mov_b64_e32 v[74:75], v[122:123]
.Latt_m2:
	s_xor_b32 s100, s100, 1
	s_andn2_b64 exec, exec, s[38:39]
	s_cbranch_execz .LBB0_187
.LBB0_301:
	v_cmp_lt_i32_e64 s[36:37], 2, v138
	s_and_saveexec_b64 s[2:3], s[36:37]
	s_cbranch_execz .Latt_noload
	v_subrev_u32_e32 v252, 32, v176
	v_mov_b32_e32 v253, v177
	v_add_u32_e32 v36, v137, v252
	v_mad_u64_u32 v[36:37], s[6:7], v36, s13, v[128:129]
	v_mov_b32_e32 v135, v177
	v_mov_b32_e32 v131, v177
	v_lshl_add_u64 v[38:39], v[252:253], 1, v[132:133]
	v_lshl_add_u64 v[252:253], v[38:39], 0, v[130:131]
	v_lshl_add_u64 v[38:39], v[38:39], 0, v[134:135]
	s_cmp_eq_u32 s100, 0
	s_cbranch_scc0 .Latt_l1
	global_load_dwordx4 v[104:107], v[36:37], off offset:512
	global_load_dwordx4 v[100:103], v[36:37], off offset:544
	global_load_dwordx4 v[96:99], v[36:37], off offset:576
	global_load_dwordx4 v[92:95], v[36:37], off offset:608
	global_load_dwordx4 v[108:111], v[38:39], off offset:16
	global_load_dwordx4 v[116:119], v[38:39], off
	global_load_dwordx4 v[112:115], v[252:253], off offset:16
	global_load_dwordx4 v[120:123], v[252:253], off
	s_branch .LBB0_303
.Latt_l1:
	global_load_dwordx4 v[220:223], v[36:37], off offset:512
	global_load_dwordx4 v[224:227], v[36:37], off offset:544
	global_load_dwordx4 v[228:231], v[36:37], off offset:576
	global_load_dwordx4 v[232:235], v[36:37], off offset:608
	global_load_dwordx4 v[236:239], v[38:39], off offset:16
	global_load_dwordx4 v[240:243], v[38:39], off
	global_load_dwordx4 v[244:247], v[252:253], off offset:16
	global_load_dwordx4 v[248:251], v[252:253], off

.Latt_noload:
	s_waitcnt vmcnt(0)
	s_branch .LBB0_303
